# sample_ml: gate and n0 loads issued by all lanes (wrapped indices) ahead of the state loads, counted waits in the masked blocks
# baseline (speedup 1.0000x reference)
; __device__ __forceinline__ float bf_lo(unsigned u) { return __uint_as_float(u << 16); }
; __device__ __forceinline__ float bf_hi(unsigned u) { return __uint_as_float(u & 0xffff0000u); }
; __device__ __forceinline__ float logsig_f(float x) { return fminf(x, 0.f) - log1pf(__expf(-fabsf(x))); }
; __device__ __forceinline__ void sample_ml(const Params& p, unsigned char* smem, int job) {
;     ...
;     {
;         const int t = tid >> 6, c = tid & 63;
;         const size_t r = (size_t)(rowb + t) * N1P;
;         const unsigned qq = *(const unsigned*)(U + r + UC_Q + h * 128 + 2 * c), kk = *(const unsigned*)(U + r + UC_K + h * 128 + 2 * c);
;         const u32x2 vv = *(const u32x2*)(U + r + UC_V + h * 256 + 4 * c);
;         qs[t * 128 + 2 * c] = bf_lo(qq); qs[t * 128 + 2 * c + 1] = bf_hi(qq);
;         ks[t * 128 + 2 * c] = bf_lo(kk) * 0.08838834764831845f; ks[t * 128 + 2 * c + 1] = bf_hi(kk) * 0.08838834764831845f;
;         *(f32x4*)(vs + t * 256 + 4 * c) = (f32x4){bf_lo(vv[0]), bf_hi(vv[0]), bf_lo(vv[1]), bf_hi(vv[1])};
;         if (tid < 8) { sig[tid] = SF[(size_t)(rowb + tid) * 64 + 32 + h] + p.in[17][h]; slf[tid] = logsig_f(SF[(size_t)(rowb + tid) * 64 + 40 + h] + p.in[18][h]); }
;         if (tid >= 128 && tid < 256) n0v[tid - 128] = p.in[5][(size_t)(b * 8 + h) * 128 + tid - 128];
.LBB0_715:
	v_mov_b32_e32 v116, v151
	s_and_b32 s0, s2, -8
	s_add_i32 s29, s0, 0x2000
	v_ashrrev_i32_e32 v10, 6, v116
	s_and_b32 s28, s2, 7
	v_add_u32_e32 v6, s29, v10
	s_waitcnt lgkmcnt(0)
	v_mov_b64_e32 v[4:5], s[18:19]
	v_and_b32_e32 v132, 63, v116
	v_mad_i64_i32 v[4:5], s[4:5], v6, s45, v[4:5]
	s_lshl_b32 s96, s28, 8
	v_lshl_add_u64 v[6:7], v[4:5], 0, s[96:97]
	v_lshlrev_b32_e32 v148, 2, v132
	v_lshl_add_u64 v[6:7], v[6:7], 0, v[148:149]
	s_movk_i32 s1, 0x2000
	v_add_co_u32_e32 v6, vcc, s1, v6
	s_lshl_b32 s4, s28, 9
	s_nop 0
	v_addc_co_u32_e32 v7, vcc, 0, v7, vcc
	s_mov_b32 s5, s97
	global_load_dword v11, v[6:7], off offset:1088
	global_load_dword v13, v[6:7], off offset:3136
	v_lshl_add_u64 v[4:5], v[4:5], 0, s[4:5]
	v_lshlrev_b32_e32 v6, 3, v132
	v_mov_b32_e32 v7, v149
	v_lshl_add_u64 v[4:5], v[4:5], 0, v[6:7]
	s_movk_i32 s1, 0x3000
	v_add_co_u32_e32 v4, vcc, s1, v4
	v_lshl_or_b32 v6, v10, 9, v6
	s_nop 0
	v_addc_co_u32_e32 v5, vcc, 0, v5, vcc
	global_load_dwordx2 v[8:9], v[4:5], off offset:1088
	v_readfirstlane_b32 s1, v10
	s_nop 0
	s_add_i32 s4, s1, s29
	s_mul_hi_i32 s5, s4, 0x5600
	s_mul_i32 s4, s4, 0x5600
	s_add_u32 s4, s18, s4
	s_addc_u32 s5, s19, s5
	s_lshl_b32 s6, s96, 1
	s_add_u32 s4, s4, s6
	s_addc_u32 s5, s5, 0
	s_add_u32 s4, s4, 0x4000
	s_addc_u32 s5, s5, 0
	v_lshlrev_b32_e32 v218, 1, v148
	v_mov_b32_e32 v219, v149
	v_lshl_add_u64 v[218:219], s[4:5], 0, v[218:219]
	global_load_dwordx2 v[220:221], v[218:219], off offset:1120
	s_ashr_i32 s3, s2, 31
	v_and_b32_e32 v222, 7, v116
	v_add_u32_e32 v222, s29, v222
	v_mov_b32_e32 v223, v149
	v_lshlrev_b64 v[222:223], 8, v[222:223]
	v_lshl_add_u64 v[222:223], s[20:21], 0, v[222:223]
	s_lshl_b32 s6, s28, 2
	s_mov_b32 s7, s97
	v_lshl_add_u64 v[222:223], v[222:223], 0, s[6:7]
	v_mov_b32_e32 v228, s6
	v_mov_b32_e32 v229, v149
	v_readlane_b32 s4, v255, 13
	v_readlane_b32 s5, v255, 14
	s_nop 0
	v_lshl_add_u64 v[224:225], s[4:5], 0, v[228:229]
	v_readlane_b32 s4, v255, 15
	v_readlane_b32 s5, v255, 16
	s_nop 0
	v_lshl_add_u64 v[226:227], s[4:5], 0, v[228:229]
	v_readlane_b32 s4, v254, 53
	v_readlane_b32 s5, v254, 54
	v_and_b32_e32 v230, 0x7f, v116
	v_lshlrev_b32_e32 v230, 2, v230
	v_mov_b32_e32 v231, v149
	v_lshl_add_u64 v[230:231], s[4:5], 0, v[230:231]
	s_lshl_b64 s[6:7], s[2:3], 9
	v_lshl_add_u64 v[230:231], v[230:231], 0, s[6:7]
	global_load_dword v232, v[222:223], off offset:128
	global_load_dword v233, v[224:225], off
	global_load_dword v234, v[222:223], off offset:160
	global_load_dword v235, v[226:227], off
	global_load_dword v236, v[230:231], off
	s_lshl_b32 s1, s1, 4
	s_lshl_b64 s[4:5], s[2:3], 7
	s_add_u32 s6, s4, s1
	s_addc_u32 s7, s5, 0
	s_lshl_b64 s[6:7], s[6:7], 8
	v_readlane_b32 s4, v254, 51
	v_readlane_b32 s5, v254, 52
	v_mov_b32_e32 v215, s7
	v_or_b32_e32 v214, s6, v148
	s_movk_i32 s6, 0x2000
	s_mov_b32 s7, 0
	v_lshl_add_u64 v[214:215], v[214:215], 2, s[4:5]
	v_lshl_add_u64 v[216:217], v[214:215], 0, s[6:7]
	global_load_dwordx4 v[96:99], v[214:215], off nt
	global_load_dwordx4 v[92:95], v[214:215], off offset:1024 nt
	global_load_dwordx4 v[88:91], v[214:215], off offset:2048 nt
	global_load_dwordx4 v[84:87], v[214:215], off offset:3072 nt
	global_load_dwordx4 v[76:79], v[216:217], off offset:-3072 nt
	global_load_dwordx4 v[72:75], v[216:217], off offset:-2048 nt
	global_load_dwordx4 v[80:83], v[216:217], off offset:-4096 nt
	global_load_dwordx4 v[64:67], v[216:217], off nt
	global_load_dwordx4 v[60:63], v[216:217], off offset:1024 nt
	global_load_dwordx4 v[56:59], v[216:217], off offset:2048 nt
	global_load_dwordx4 v[52:55], v[216:217], off offset:3072 nt
	global_load_dwordx4 v[68:71], v[216:217], off offset:-1024 nt
	v_lshlrev_b32_e32 v4, 10, v10
	v_lshlrev_b32_e32 v5, 4, v132
	v_cmp_gt_i32_e32 vcc, 8, v116
	v_readfirstlane_b32 s30, v10
	v_add3_u32 v14, 0, v4, v5
	v_add_u32_e32 v15, 0, v6
	v_lshl_add_u32 v133, v116, 2, 0
	s_waitcnt vmcnt(20)
	v_lshlrev_b32_e32 v10, 16, v11
	s_waitcnt vmcnt(19)
	v_lshlrev_b32_e32 v12, 16, v13
	v_and_b32_e32 v13, 0xffff0000, v13
	v_and_b32_e32 v11, 0xffff0000, v11
	s_waitcnt vmcnt(18)
	v_lshlrev_b32_e32 v4, 16, v8
	v_and_b32_e32 v5, 0xffff0000, v8
	v_lshlrev_b32_e32 v6, 16, v9
	v_and_b32_e32 v7, 0xffff0000, v9
	v_pk_mul_f32 v[8:9], v[12:13], s[90:91] op_sel_hi:[1,0]
	ds_write2st64_b64 v15, v[10:11], v[8:9] offset1:8
	ds_write_b128 v14, v[4:7] offset:8192
	s_and_saveexec_b64 s[4:5], vcc
	s_cbranch_execz .LBB0_717
; __device__ __forceinline__ float logsig_f(float x) { return fminf(x, 0.f) - log1pf(__expf(-fabsf(x))); }
; __device__ __forceinline__ void sample_ml(const Params& p, unsigned char* smem, int job) {
;     ...
;         if (tid < 8) { sig[tid] = SF[(size_t)(rowb + tid) * 64 + 32 + h] + p.in[17][h]; slf[tid] = logsig_f(SF[(size_t)(rowb + tid) * 64 + 40 + h] + p.in[18][h]); }
;         if (tid >= 128 && tid < 256) n0v[tid - 128] = p.in[5][(size_t)(b * 8 + h) * 128 + tid - 128];
	v_add_u32_e32 v4, s29, v116
	v_ashrrev_i32_e32 v5, 31, v4
	v_lshlrev_b64 v[4:5], 8, v[4:5]
	v_lshl_add_u64 v[4:5], s[20:21], 0, v[4:5]
	s_lshl_b32 s6, s28, 2
	s_mov_b32 s7, s97
	v_readlane_b32 s56, v255, 11
	v_lshl_add_u64 v[6:7], v[4:5], 0, s[6:7]
	v_mov_b32_e32 v5, s6
	v_readlane_b32 s58, v255, 13
	v_readlane_b32 s59, v255, 14
	v_readlane_b32 s60, v255, 15
	v_readlane_b32 s61, v255, 16
	s_mov_b32 s1, 0xbfb8aa3b
	s_mov_b32 s6, 0x3f317218
	s_nop 0
	s_nop 0
	v_readlane_b32 s57, v255, 12
	v_readlane_b32 s62, v255, 17
	v_readlane_b32 s63, v255, 18
	v_readlane_b32 s64, v255, 19
	v_readlane_b32 s65, v255, 20
	v_readlane_b32 s66, v255, 21
	v_readlane_b32 s67, v255, 22
	v_readlane_b32 s68, v255, 23
	v_readlane_b32 s69, v255, 24
	v_readlane_b32 s70, v255, 25
	v_readlane_b32 s71, v255, 26
	s_waitcnt vmcnt(15)
	v_add_f32_e32 v4, v232, v233
	s_waitcnt vmcnt(13)
	v_add_f32_e32 v6, v234, v235
	v_min_f32_e32 v5, 0, v6
	v_mul_f32_e64 v6, |v6|, s1
	v_exp_f32_e32 v6, v6
	s_mov_b32 s1, 0x3f2aaaab
	v_add_f32_e32 v7, 1.0, v6
	v_add_f32_e32 v8, -1.0, v7
	v_sub_f32_e32 v9, v8, v7
	v_add_f32_e32 v9, 1.0, v9
	v_sub_f32_e32 v8, v6, v8
	v_add_f32_e32 v10, v8, v9
	v_frexp_mant_f32_e32 v8, v7
	v_cmp_gt_f32_e32 vcc, s1, v8
	v_cvt_f64_f32_e32 v[8:9], v7
	v_frexp_exp_i32_f64_e32 v8, v[8:9]
	v_subbrev_co_u32_e32 v8, vcc, 0, v8, vcc
	v_sub_u32_e32 v9, 0, v8
	v_ldexp_f32 v7, v7, v9
	v_ldexp_f32 v9, v10, v9
	v_add_f32_e32 v10, -1.0, v7
	v_add_f32_e32 v11, 1.0, v10
	v_sub_f32_e32 v11, v7, v11
	v_add_f32_e32 v11, v9, v11
	v_add_f32_e32 v12, v10, v11
	v_sub_f32_e32 v10, v12, v10
	v_sub_f32_e32 v10, v11, v10
	v_add_f32_e32 v11, 1.0, v7
	v_add_f32_e32 v13, -1.0, v11
	v_sub_f32_e32 v7, v7, v13
	v_add_f32_e32 v7, v9, v7
	v_add_f32_e32 v9, v11, v7
	v_sub_f32_e32 v11, v9, v11
	v_sub_f32_e32 v7, v7, v11
	v_rcp_f32_e32 v11, v9
	v_cvt_f32_i32_e32 v8, v8
	s_mov_b32 s1, 0x7f800000
	v_cmp_neq_f32_e32 vcc, s1, v6
	v_mul_f32_e32 v13, v12, v11
	v_mul_f32_e32 v14, v9, v13
	v_fma_f32 v15, v13, v9, -v14
	v_fmac_f32_e32 v15, v13, v7
	v_add_f32_e32 v16, v14, v15
	v_sub_f32_e32 v17, v12, v16
	v_sub_f32_e32 v12, v12, v17
	v_sub_f32_e32 v14, v16, v14
	v_sub_f32_e32 v12, v12, v16
	v_add_f32_e32 v10, v10, v12
	v_sub_f32_e32 v12, v14, v15
	v_add_f32_e32 v10, v12, v10
	v_add_f32_e32 v12, v17, v10
	v_mul_f32_e32 v14, v11, v12
	v_mul_f32_e32 v15, v9, v14
	v_fma_f32 v9, v14, v9, -v15
	v_fmac_f32_e32 v9, v14, v7
	v_sub_f32_e32 v7, v17, v12
	v_add_f32_e32 v7, v10, v7
	v_add_f32_e32 v10, v15, v9
	v_sub_f32_e32 v16, v12, v10
	v_sub_f32_e32 v12, v12, v16
	v_sub_f32_e32 v15, v10, v15
	v_sub_f32_e32 v10, v12, v10
	v_add_f32_e32 v7, v7, v10
	v_sub_f32_e32 v9, v15, v9
	v_add_f32_e32 v7, v9, v7
	v_add_f32_e32 v9, v13, v14
	v_add_f32_e32 v7, v16, v7
	v_sub_f32_e32 v10, v9, v13
	v_mul_f32_e32 v7, v11, v7
	v_sub_f32_e32 v10, v14, v10
	v_add_f32_e32 v7, v10, v7
	v_mul_f32_e32 v13, 0x3f317218, v8
	v_add_f32_e32 v10, v9, v7
	v_fma_f32 v14, v8, s6, -v13
	v_mul_f32_e32 v11, v10, v10
	v_fmac_f32_e32 v14, 0xb102e308, v8
	v_sub_f32_e32 v8, v10, v9
	v_fmamk_f32 v12, v11, 0x3e9b6dac, v150
	v_sub_f32_e32 v7, v7, v8
	v_add_f32_e32 v8, v13, v14
	v_fmaak_f32 v12, v11, v12, 0x3f2aaada
	v_sub_f32_e32 v9, v8, v13
	v_ldexp_f32 v13, v10, 1
	v_mul_f32_e32 v10, v10, v11
	v_mul_f32_e32 v10, v10, v12
	v_add_f32_e32 v11, v13, v10
	v_sub_f32_e32 v12, v11, v13
	v_ldexp_f32 v7, v7, 1
	v_sub_f32_e32 v10, v10, v12
	v_add_f32_e32 v7, v7, v10
	v_add_f32_e32 v10, v11, v7
	v_sub_f32_e32 v11, v10, v11
	v_sub_f32_e32 v7, v7, v11
	v_add_f32_e32 v11, v8, v10
	v_sub_f32_e32 v12, v11, v8
	v_sub_f32_e32 v13, v11, v12
	v_sub_f32_e32 v9, v14, v9
	v_sub_f32_e32 v8, v8, v13
	v_sub_f32_e32 v10, v10, v12
	v_add_f32_e32 v8, v10, v8
	v_add_f32_e32 v10, v9, v7
	v_sub_f32_e32 v12, v10, v9
	v_sub_f32_e32 v13, v10, v12
	v_sub_f32_e32 v9, v9, v13
	v_sub_f32_e32 v7, v7, v12
	v_add_f32_e32 v8, v10, v8
	v_add_f32_e32 v7, v7, v9
	v_add_f32_e32 v9, v11, v8
	v_sub_f32_e32 v10, v9, v11
	v_sub_f32_e32 v8, v8, v10
	v_add_f32_e32 v7, v7, v8
	v_add_f32_e32 v7, v9, v7
	v_cndmask_b32_e32 v7, v210, v7, vcc
	v_cmp_ngt_f32_e32 vcc, -1.0, v6
	s_mov_b32 s1, 0x33800000
	s_nop 0
	v_cndmask_b32_e32 v7, v211, v7, vcc
	v_cmp_neq_f32_e32 vcc, -1.0, v6
	s_nop 1
	v_cndmask_b32_e32 v7, v212, v7, vcc
	v_cmp_lt_f32_e64 vcc, |v6|, s1
	s_nop 1
	v_cndmask_b32_e32 v6, v7, v6, vcc
	v_sub_f32_e32 v5, v5, v6
	v_add_u32_e32 v6, 0x4000, v133
	ds_write2_b32 v6, v4, v5 offset0:64 offset1:72
.LBB0_717:
	s_or_b64 exec, exec, s[4:5]
	v_and_b32_e32 v4, 0xffffff80, v116
	s_movk_i32 s1, 0x80
	v_cmp_eq_u32_e32 vcc, s1, v4
	s_ashr_i32 s3, s2, 31
	s_and_saveexec_b64 s[4:5], vcc
	s_cbranch_execz .LBB0_719
	v_readlane_b32 s56, v254, 43
	s_lshl_b64 s[6:7], s[2:3], 9
	v_readlane_b32 s66, v254, 53
	v_readlane_b32 s67, v254, 54
	s_add_u32 s6, s66, s6
	v_mov_b32_e32 v117, v149
	s_addc_u32 s7, s67, s7
	v_lshl_add_u64 v[4:5], v[116:117], 2, s[6:7]
	v_readlane_b32 s57, v254, 44
	v_readlane_b32 s58, v254, 45
	v_readlane_b32 s59, v254, 46
	v_readlane_b32 s60, v254, 47
	v_readlane_b32 s61, v254, 48
	v_readlane_b32 s62, v254, 49
	v_readlane_b32 s63, v254, 50
	v_readlane_b32 s64, v254, 51
	v_readlane_b32 s65, v254, 52
	v_readlane_b32 s68, v254, 55
	v_readlane_b32 s69, v254, 56
	v_readlane_b32 s70, v254, 57
	v_readlane_b32 s71, v254, 58
	s_waitcnt vmcnt(12)
	ds_write_b32 v133, v236 offset:16256
